# flat->global + per-XCD tile queues hand out 8-tile patches instead of 64-tile patches (balances XCDs in phases with few tiles)
# speedup vs baseline: 1.0279x; 1.0180x over previous
; DI int TID() { int t = threadIdx.x; asm volatile("" : "+v"(t)); return t; }
; DI void phase_gemm(const Params& p, int g, int kind, char* smem, float* rsl, int* s_item, int vlo, int vhi, int cslot) {
;     ...
;   auto fetch = [&](TD& d) {
;     for (;;) {
;       __syncthreads();
;       if (TID() == 0) *s_item = atomicAdd(qctr, 1);
;       __syncthreads();
;       const int kq = *s_item;
;       const int tile = ((kq >> 6) * 8 + xcd) * 64 + (kq & 63);
;       if (tile >= total) { d.ok = false; return; }
;       const int strip = tile / (MT * 8), rem = tile - strip * (MT * 8);
;       const int wdt = min(8, nvt - strip * 8);
;       const int mt = rem / wdt, vt = vlo + strip * 8 + rem % wdt;
;       d.nt = kind == 0 ? nt_map0(vt) : vt; d.m0 = mt * 128; d.n0 = d.nt * 256;
;       if (kind == 0) { d.A = (const bfu*)(G + L0_H) + (long)d.m0 * 2048; d.Bt = P_WA + (long)d.n0 * 2048; d.K = 2048; }
.LBB0_187:
	s_or_b64 exec, exec, s[2:3]
	v_mov_b32_e32 v0, 0x122d0
	s_waitcnt lgkmcnt(0)
	s_barrier
	ds_read_b32 v0, v0
	s_waitcnt lgkmcnt(0)
	v_readfirstlane_b32 s2, v0
	s_and_b32 s3, s2, 0xfffffff8
	s_or_b32 s3, s3, s33
	s_and_b32 s2, s2, 7
	s_lshl_b32 s3, s3, 3
	s_or_b32 s2, s3, s2
	s_cmpk_lt_i32 s2, 0x3f0
	s_cselect_b64 s[4:5], -1, 0
	s_cmpk_gt_i32 s2, 0x3ef
	s_cbranch_scc1 .LBB0_189
	s_mul_hi_i32 s3, s2, 0x38e38e39
	s_lshr_b32 s6, s3, 31
	s_ashr_i32 s3, s3, 6
	s_add_i32 s3, s3, s6
	s_lshl_b32 s6, s3, 3
	s_sub_i32 s7, 28, s6
	s_min_u32 s7, s7, 8
	v_cvt_f32_ubyte0_e32 v0, s7
	v_rcp_iflag_f32_e32 v0, v0
	s_sub_i32 s9, 0, s7
	s_mulk_i32 s3, 0xfee0
	s_add_i32 s3, s3, s2
	v_mul_f32_e32 v0, 0x4f7ffffe, v0
	v_cvt_u32_f32_e32 v0, v0
	s_abs_i32 s8, s3
	s_ashr_i32 s2, s3, 31
	v_readfirstlane_b32 s10, v0
	s_mul_i32 s9, s9, s10
	s_mul_hi_u32 s9, s10, s9
	s_add_i32 s10, s10, s9
	s_mul_hi_u32 s9, s8, s10
	s_mul_i32 s10, s9, s7
	s_sub_i32 s8, s8, s10
	s_add_i32 s10, s9, 1
	s_sub_i32 s11, s8, s7
	s_cmp_ge_u32 s8, s7
	s_cselect_b32 s9, s10, s9
	s_cselect_b32 s8, s11, s8
	s_add_i32 s10, s9, 1
	s_cmp_ge_u32 s8, s7
	s_cselect_b32 s8, s10, s9
	s_xor_b32 s8, s8, s2
	s_sub_i32 s2, s8, s2
	s_mul_i32 s7, s2, s7
	s_sub_i32 s3, s3, s7
	s_add_i32 s3, s3, s6
	s_add_i32 s6, s3, 24
	s_sub_i32 s7, s3, 17
	s_cmp_lg_u32 s3, 16
	s_cselect_b32 s7, s7, 64
	s_cmp_lt_i32 s3, 16
	s_cselect_b32 s94, s6, s7
	s_lshl_b32 s30, s2, 7
	s_ashr_i32 s31, s30, 31
	s_lshl_b32 s34, s94, 8
	s_lshl_b64 s[2:3], s[30:31], 12
	s_add_u32 s2, s0, s2
	s_addc_u32 s3, s1, s3
	s_add_u32 s36, s2, 0xea00000
	s_addc_u32 s37, s3, 0
	s_ashr_i32 s35, s34, 31
	s_lshl_b64 s[2:3], s[34:35], 12
	v_readlane_b32 s6, v254, 13
	s_add_u32 s38, s6, s2
	v_readlane_b32 s2, v254, 14
	s_addc_u32 s39, s2, s3
	v_cndmask_b32_e64 v0, 0, 1, s[4:5]
	v_cmp_ne_u32_e64 s[2:3], 1, v0
	s_andn2_b64 vcc, exec, s[4:5]
	s_cbranch_vccnz .LBB0_191
	s_branch .LBB0_190

; DI int TID() { int t = threadIdx.x; asm volatile("" : "+v"(t)); return t; }
; DI void phase_gemm(const Params& p, int g, int kind, char* smem, float* rsl, int* s_item, int vlo, int vhi, int cslot) {
;     ...
;   auto fetch = [&](TD& d) {
;     for (;;) {
;       __syncthreads();
;       if (TID() == 0) *s_item = atomicAdd(qctr, 1);
;       __syncthreads();
;       const int kq = *s_item;
;       const int tile = ((kq >> 6) * 8 + xcd) * 64 + (kq & 63);
;       if (tile >= total) { d.ok = false; return; }
;       const int strip = tile / (MT * 8), rem = tile - strip * (MT * 8);
;       const int wdt = min(8, nvt - strip * 8);
;       const int mt = rem / wdt, vt = vlo + strip * 8 + rem % wdt;
;       d.nt = kind == 0 ? nt_map0(vt) : vt; d.m0 = mt * 128; d.n0 = d.nt * 256;
;       if (kind == 0) { d.A = (const bfu*)(G + L0_H) + (long)d.m0 * 2048; d.Bt = P_WA + (long)d.n0 * 2048; d.K = 2048; }
.LBB0_201:
	s_or_b64 exec, exec, s[2:3]
	s_waitcnt lgkmcnt(0)
	s_barrier
	ds_read_b32 v176, v183
	s_waitcnt lgkmcnt(0)
	v_readfirstlane_b32 s1, v176
	s_and_b32 s2, s1, 0xfffffff8
	s_or_b32 s2, s2, s33
	s_and_b32 s1, s1, 7
	s_lshl_b32 s2, s2, 3
	s_or_b32 s1, s2, s1
	s_cmpk_lt_i32 s1, 0x3f0
	s_cselect_b64 s[2:3], -1, 0
	s_cmpk_gt_i32 s1, 0x3ef
	s_cselect_b64 s[50:51], -1, 0
	s_and_b64 vcc, exec, s[50:51]
	s_cbranch_vccnz .LBB0_203
	s_mul_hi_i32 s4, s1, 0x38e38e39
	s_lshr_b32 s5, s4, 31
	s_ashr_i32 s4, s4, 6
	s_add_i32 s4, s4, s5
	s_lshl_b32 s5, s4, 3
	s_sub_i32 s6, 28, s5
	s_min_u32 s6, s6, 8
	v_cvt_f32_ubyte0_e32 v176, s6
	v_rcp_iflag_f32_e32 v176, v176
	s_sub_i32 s8, 0, s6
	s_mulk_i32 s4, 0xfee0
	s_add_i32 s4, s4, s1
	v_mul_f32_e32 v176, 0x4f7ffffe, v176
	v_cvt_u32_f32_e32 v176, v176
	s_abs_i32 s7, s4
	s_ashr_i32 s1, s4, 31
	v_readfirstlane_b32 s9, v176
	s_mul_i32 s8, s8, s9
	s_mul_hi_u32 s8, s9, s8
	s_add_i32 s9, s9, s8
	s_mul_hi_u32 s8, s7, s9
	s_mul_i32 s9, s8, s6
	s_sub_i32 s7, s7, s9
	s_add_i32 s9, s8, 1
	s_sub_i32 s10, s7, s6
	s_cmp_ge_u32 s7, s6
	s_cselect_b32 s8, s9, s8
	s_cselect_b32 s7, s10, s7
	s_add_i32 s9, s8, 1
	s_cmp_ge_u32 s7, s6
	s_cselect_b32 s7, s9, s8
	s_xor_b32 s7, s7, s1
	s_sub_i32 s1, s7, s1
	s_mul_i32 s6, s1, s6
	s_sub_i32 s4, s4, s6
	s_add_i32 s4, s4, s5
	s_add_i32 s5, s4, 24
	s_sub_i32 s6, s4, 17
	s_cmp_lg_u32 s4, 16
	s_cselect_b32 s6, s6, 64
	s_cmp_lt_i32 s4, 16
	s_cselect_b32 s94, s5, s6
	s_lshl_b32 s30, s1, 7
	s_ashr_i32 s31, s30, 31
	s_lshl_b32 s34, s94, 8
	s_lshl_b64 s[4:5], s[30:31], 12
	s_add_u32 s36, s61, s4
	s_addc_u32 s37, s64, s5
	s_ashr_i32 s35, s34, 31
	s_lshl_b64 s[4:5], s[34:35], 12
	v_readlane_b32 s1, v254, 13
	s_add_u32 s38, s1, s4
	v_readlane_b32 s1, v254, 14
	s_addc_u32 s39, s1, s5

; DI int TID() { int t = threadIdx.x; asm volatile("" : "+v"(t)); return t; }
; DI void phase_gemm(const Params& p, int g, int kind, char* smem, float* rsl, int* s_item, int vlo, int vhi, int cslot) {
;     ...
;   auto fetch = [&](TD& d) {
;     for (;;) {
;       __syncthreads();
;       if (TID() == 0) *s_item = atomicAdd(qctr, 1);
;       __syncthreads();
;       const int kq = *s_item;
;       const int tile = ((kq >> 6) * 8 + xcd) * 64 + (kq & 63);
;       if (tile >= total) { d.ok = false; return; }
;       const int strip = tile / (MT * 8), rem = tile - strip * (MT * 8);
;       const int wdt = min(8, nvt - strip * 8);
;       const int mt = rem / wdt, vt = vlo + strip * 8 + rem % wdt;
;       d.nt = kind == 0 ? nt_map0(vt) : vt; d.m0 = mt * 128; d.n0 = d.nt * 256;
;       if (kind == 0) { d.A = (const bfu*)(G + L0_H) + (long)d.m0 * 2048; d.Bt = P_WA + (long)d.n0 * 2048; d.K = 2048; }
.LBB0_518:
	s_or_b64 exec, exec, s[2:3]
	s_waitcnt lgkmcnt(0)
	s_barrier
	ds_read_b32 v0, v191
	s_waitcnt lgkmcnt(0)
	v_readfirstlane_b32 s2, v0
	s_and_b32 s3, s2, 0xfffffff8
	s_or_b32 s3, s3, s33
	s_and_b32 s2, s2, 7
	s_lshl_b32 s3, s3, 3
	s_or_b32 s4, s3, s2
	s_cmpk_lt_i32 s4, 0x534
	s_cselect_b64 s[2:3], -1, 0
	s_cmpk_gt_i32 s4, 0x533
	s_cbranch_scc1 .LBB0_524
	s_mul_hi_i32 s5, s4, 0x38e38e39
	s_lshr_b32 s6, s5, 31
	s_ashr_i32 s5, s5, 6
	s_add_i32 s5, s5, s6
	s_lshl_b32 s7, s5, 3
	s_sub_i32 s6, 37, s7
	s_min_u32 s8, s6, 8
	v_cvt_f32_ubyte0_e32 v0, s8
	v_rcp_iflag_f32_e32 v0, v0
	s_sub_i32 s9, 0, s8
	s_mulk_i32 s5, 0xfee0
	s_add_i32 s5, s5, s4
	v_mul_f32_e32 v0, 0x4f7ffffe, v0
	v_cvt_u32_f32_e32 v0, v0
	s_abs_i32 s6, s5
	s_ashr_i32 s4, s5, 31
	v_readfirstlane_b32 s10, v0
	s_mul_i32 s9, s9, s10
	s_mul_hi_u32 s9, s10, s9
	s_add_i32 s10, s10, s9
	s_mul_hi_u32 s9, s6, s10
	s_mul_i32 s10, s9, s8
	s_sub_i32 s6, s6, s10
	s_add_i32 s10, s9, 1
	s_sub_i32 s11, s6, s8
	s_cmp_ge_u32 s6, s8
	s_cselect_b32 s9, s10, s9
	s_cselect_b32 s6, s11, s6
	s_add_i32 s10, s9, 1
	s_cmp_ge_u32 s6, s8
	s_cselect_b32 s6, s10, s9
	s_xor_b32 s6, s6, s4
	s_sub_i32 s6, s6, s4
	s_mul_i32 s4, s6, s8
	s_sub_i32 s4, s5, s4
	s_add_i32 s7, s7, s4
	s_add_i32 s7, s7, 28
	s_cmp_gt_i32 s7, 15
	s_mov_b64 s[4:5], -1
	s_cbranch_scc0 .LBB0_521
	s_cmp_lt_u32 s7, 41
	s_cselect_b32 s4, 0xffffffef, -1
	s_add_i32 s4, s4, s7
	s_cmp_lg_u32 s7, 16
	s_cselect_b32 s16, s4, 64
	s_mov_b64 s[4:5], 0

; DI int TID() { int t = threadIdx.x; asm volatile("" : "+v"(t)); return t; }
; DI void phase_gemm(const Params& p, int g, int kind, char* smem, float* rsl, int* s_item, int vlo, int vhi, int cslot) {
;     ...
;   auto fetch = [&](TD& d) {
;     for (;;) {
;       __syncthreads();
;       if (TID() == 0) *s_item = atomicAdd(qctr, 1);
;       __syncthreads();
;       const int kq = *s_item;
;       const int tile = ((kq >> 6) * 8 + xcd) * 64 + (kq & 63);
;       if (tile >= total) { d.ok = false; return; }
;       const int strip = tile / (MT * 8), rem = tile - strip * (MT * 8);
;       const int wdt = min(8, nvt - strip * 8);
;       const int mt = rem / wdt, vt = vlo + strip * 8 + rem % wdt;
;       d.nt = kind == 0 ? nt_map0(vt) : vt; d.m0 = mt * 128; d.n0 = d.nt * 256;
;       if (kind == 0) { d.A = (const bfu*)(G + L0_H) + (long)d.m0 * 2048; d.Bt = P_WA + (long)d.n0 * 2048; d.K = 2048; }
.LBB0_536:
	s_or_b64 exec, exec, s[2:3]
	s_waitcnt lgkmcnt(0)
	s_barrier
	ds_read_b32 v128, v191
	s_waitcnt lgkmcnt(0)
	v_readfirstlane_b32 s1, v128
	s_and_b32 s2, s1, 0xfffffff8
	s_or_b32 s2, s2, s33
	s_and_b32 s1, s1, 7
	s_lshl_b32 s2, s2, 3
	s_or_b32 s1, s2, s1
	s_cmpk_lt_i32 s1, 0x534
	s_cselect_b64 s[2:3], -1, 0
	s_cmpk_gt_i32 s1, 0x533
	s_cselect_b64 s[46:47], -1, 0
	s_and_b64 vcc, exec, s[46:47]
	s_cbranch_vccnz .LBB0_543
	s_mul_hi_i32 s4, s1, 0x38e38e39
	s_lshr_b32 s5, s4, 31
	s_ashr_i32 s4, s4, 6
	s_add_i32 s4, s4, s5
	s_lshl_b32 s5, s4, 3
	s_sub_i32 s6, 37, s5
	s_min_u32 s6, s6, 8
	v_cvt_f32_ubyte0_e32 v128, s6
	v_rcp_iflag_f32_e32 v128, v128
	s_sub_i32 s13, 0, s6
	s_mulk_i32 s4, 0xfee0
	s_add_i32 s4, s4, s1
	v_mul_f32_e32 v128, 0x4f7ffffe, v128
	v_cvt_u32_f32_e32 v128, v128
	s_abs_i32 s7, s4
	s_ashr_i32 s1, s4, 31
	v_readfirstlane_b32 s14, v128
	s_mul_i32 s13, s13, s14
	s_mul_hi_u32 s13, s14, s13
	s_add_i32 s14, s14, s13
	s_mul_hi_u32 s13, s7, s14
	s_mul_i32 s14, s13, s6
	s_sub_i32 s7, s7, s14
	s_add_i32 s14, s13, 1
	s_sub_i32 s15, s7, s6
	s_cmp_ge_u32 s7, s6
	s_cselect_b32 s13, s14, s13
	s_cselect_b32 s7, s15, s7
	s_add_i32 s14, s13, 1
	s_cmp_ge_u32 s7, s6
	s_cselect_b32 s7, s14, s13
	s_xor_b32 s7, s7, s1
	s_sub_i32 s1, s7, s1
	s_mul_i32 s6, s1, s6
	s_sub_i32 s4, s4, s6
	s_add_i32 s6, s5, s4
	s_add_i32 s6, s6, 28
	s_cmp_gt_i32 s6, 15
	s_mov_b64 s[4:5], -1
	s_cbranch_scc0 .LBB0_539
	s_cmp_lt_u32 s6, 41
	s_cselect_b32 s4, 0xffffffef, -1
	s_add_i32 s4, s4, s6
	s_cmp_lg_u32 s6, 16
	s_cselect_b32 s16, s4, 64
	s_mov_b64 s[4:5], 0

; DI int TID() { int t = threadIdx.x; asm volatile("" : "+v"(t)); return t; }
; DI void phase_gemm(const Params& p, int g, int kind, char* smem, float* rsl, int* s_item, int vlo, int vhi, int cslot) {
;     ...
;   auto fetch = [&](TD& d) {
;     for (;;) {
;       __syncthreads();
;       if (TID() == 0) *s_item = atomicAdd(qctr, 1);
;       __syncthreads();
;       const int kq = *s_item;
;       const int tile = ((kq >> 6) * 8 + xcd) * 64 + (kq & 63);
;       if (tile >= total) { d.ok = false; return; }
;       const int strip = tile / (MT * 8), rem = tile - strip * (MT * 8);
;       const int wdt = min(8, nvt - strip * 8);
;       const int mt = rem / wdt, vt = vlo + strip * 8 + rem % wdt;
;       d.nt = kind == 0 ? nt_map0(vt) : vt; d.m0 = mt * 128; d.n0 = d.nt * 256;
;       if (kind == 0) { d.A = (const bfu*)(G + L0_H) + (long)d.m0 * 2048; d.Bt = P_WA + (long)d.n0 * 2048; d.K = 2048; }
;       else if (kind == 1) { d.A = (const bfu*)(G + L1_H) + (long)d.m0 * 2048; d.Bt = (const bfu*)((char*)P_WA + WA_W2) + (long)d.n0 * 2048; d.K = 2048; }
;       else if (kind == 2) {
;         if (d.nt < 12) { d.A = (const bfu*)(G + L1_QL) + (long)d.m0 * 512; d.Bt = (const bfu*)((char*)P_WA + WA_UQ) + (long)d.n0 * 512; d.K = 512; }
;         else { d.n0 -= 12 * 256; d.A = (const bfu*)(G + L1_KVL) + (long)d.m0 * 256; d.Bt = (const bfu*)((char*)P_WA + WA_UKV) + (long)d.n0 * 256; d.K = 256; }
;       } else {
;         const int layer = kind - 3;
;         if (layer == 1 && (d.m0 % T) < CTX) continue;
;         d.A = (const bfu*)(G + (layer == 0 ? L0_MIX : L1_MIX)) + (long)d.m0 * 4096;
;         d.Bt = (layer == 0 ? P_WO1 : (const bfu*)((char*)P_WA + WA_WO2)) + (long)d.n0 * 4096; d.K = 4096;
;       }
.LBB0_879:
	s_or_b64 exec, exec, s[0:1]
	s_waitcnt lgkmcnt(0)
	s_barrier
	ds_read_b32 v0, v191
	s_waitcnt lgkmcnt(0)
	v_readfirstlane_b32 s0, v0
	s_and_b32 s1, s0, 0xfffffff8
	s_or_b32 s1, s1, s33
	s_and_b32 s0, s0, 7
	s_lshl_b32 s1, s1, 3
	s_or_b32 s1, s1, s0
	s_cmpk_lt_i32 s1, 0x120
	s_cselect_b64 s[2:3], -1, 0
	s_cmpk_gt_i32 s1, 0x11f
	s_cbranch_scc1 .LBB0_881
	s_mul_hi_i32 s0, s1, 0x38e38e39
	s_lshr_b32 s6, s0, 31
	s_ashr_i32 s0, s0, 6
	s_add_i32 s0, s0, s6
	s_mul_i32 s6, s0, 0xfffffee0
	s_add_i32 s1, s6, s1
	s_ashr_i32 s6, s1, 31
	s_lshr_b32 s6, s6, 29
	s_add_i32 s6, s1, s6
	s_and_b32 s7, s6, 0xfffff8
	s_lshl_b32 s6, s6, 4
	s_sub_i32 s1, s1, s7
	s_and_b32 s14, s6, 0xffffff80
	s_lshl_b32 s0, s0, 11
	s_lshl_b32 s1, s1, 8
	s_ashr_i32 s15, s14, 31
	s_add_i32 s0, s0, s1
	s_lshl_b64 s[6:7], s[14:15], 13
	s_add_u32 s1, s12, s6
	s_addc_u32 s6, s13, s7
	s_add_u32 s8, s1, 0xfc00000
	s_addc_u32 s9, s6, 0
	s_ashr_i32 s1, s0, 31
	s_lshl_b64 s[6:7], s[0:1], 13
	v_readlane_b32 s1, v254, 11
	s_add_u32 s10, s1, s6
	v_readlane_b32 s1, v254, 12
	s_addc_u32 s11, s1, s7

; DI int TID() { int t = threadIdx.x; asm volatile("" : "+v"(t)); return t; }
; DI void phase_gemm(const Params& p, int g, int kind, char* smem, float* rsl, int* s_item, int vlo, int vhi, int cslot) {
;     ...
;   auto fetch = [&](TD& d) {
;     for (;;) {
;       __syncthreads();
;       if (TID() == 0) *s_item = atomicAdd(qctr, 1);
;       __syncthreads();
;       const int kq = *s_item;
;       const int tile = ((kq >> 6) * 8 + xcd) * 64 + (kq & 63);
;       if (tile >= total) { d.ok = false; return; }
;       const int strip = tile / (MT * 8), rem = tile - strip * (MT * 8);
;       const int wdt = min(8, nvt - strip * 8);
;       const int mt = rem / wdt, vt = vlo + strip * 8 + rem % wdt;
;       d.nt = kind == 0 ? nt_map0(vt) : vt; d.m0 = mt * 128; d.n0 = d.nt * 256;
;       if (kind == 0) { d.A = (const bfu*)(G + L0_H) + (long)d.m0 * 2048; d.Bt = P_WA + (long)d.n0 * 2048; d.K = 2048; }
;       else if (kind == 1) { d.A = (const bfu*)(G + L1_H) + (long)d.m0 * 2048; d.Bt = (const bfu*)((char*)P_WA + WA_W2) + (long)d.n0 * 2048; d.K = 2048; }
;       else if (kind == 2) {
;         if (d.nt < 12) { d.A = (const bfu*)(G + L1_QL) + (long)d.m0 * 512; d.Bt = (const bfu*)((char*)P_WA + WA_UQ) + (long)d.n0 * 512; d.K = 512; }
;         else { d.n0 -= 12 * 256; d.A = (const bfu*)(G + L1_KVL) + (long)d.m0 * 256; d.Bt = (const bfu*)((char*)P_WA + WA_UKV) + (long)d.n0 * 256; d.K = 256; }
;       } else {
;         const int layer = kind - 3;
;         if (layer == 1 && (d.m0 % T) < CTX) continue;
;         d.A = (const bfu*)(G + (layer == 0 ? L0_MIX : L1_MIX)) + (long)d.m0 * 4096;
;         d.Bt = (layer == 0 ? P_WO1 : (const bfu*)((char*)P_WA + WA_WO2)) + (long)d.n0 * 4096; d.K = 4096;
;       }
.LBB0_892:
	s_or_b64 exec, exec, s[2:3]
	s_waitcnt lgkmcnt(0)
	s_barrier
	ds_read_b32 v128, v191
	s_waitcnt lgkmcnt(0)
	v_readfirstlane_b32 s1, v128
	s_and_b32 s2, s1, 0xfffffff8
	s_or_b32 s2, s2, s33
	s_and_b32 s1, s1, 7
	s_lshl_b32 s2, s2, 3
	s_or_b32 s1, s2, s1
	s_cmpk_lt_i32 s1, 0x120
	s_cselect_b64 s[2:3], -1, 0
	s_cmpk_gt_i32 s1, 0x11f
	s_cselect_b64 s[16:17], -1, 0
	s_and_b64 vcc, exec, s[16:17]
	s_cbranch_vccnz .LBB0_894
	s_mul_hi_i32 s6, s1, 0x38e38e39
	s_lshr_b32 s7, s6, 31
	s_ashr_i32 s6, s6, 6
	s_add_i32 s7, s6, s7
	s_mul_i32 s6, s7, 0xfffffee0
	s_add_i32 s1, s6, s1
	s_ashr_i32 s6, s1, 31
	s_lshr_b32 s6, s6, 29
	s_add_i32 s6, s1, s6
	s_and_b32 s8, s6, 0xfffff8
	s_sub_i32 s1, s1, s8
	s_lshl_b32 s6, s6, 4
	s_and_b32 s6, s6, 0xffffff80
	s_lshl_b32 s7, s7, 11
	s_lshl_b32 s1, s1, 8
	s_add_i32 s12, s7, s1
	s_ashr_i32 s7, s6, 31
	s_lshl_b64 s[8:9], s[6:7], 13
	s_add_u32 s8, s26, s8
	s_addc_u32 s9, s27, s9
	s_ashr_i32 s13, s12, 31
	s_lshl_b64 s[10:11], s[12:13], 13
	v_readlane_b32 s1, v254, 11
	s_add_u32 s10, s1, s10
	v_readlane_b32 s1, v254, 12
	s_addc_u32 s11, s1, s11

; DI int TID() { int t = threadIdx.x; asm volatile("" : "+v"(t)); return t; }
; DI void phase_gemm(const Params& p, int g, int kind, char* smem, float* rsl, int* s_item, int vlo, int vhi, int cslot) {
;     ...
;   auto fetch = [&](TD& d) {
;     for (;;) {
;       __syncthreads();
;       if (TID() == 0) *s_item = atomicAdd(qctr, 1);
;       __syncthreads();
;       const int kq = *s_item;
;       const int tile = ((kq >> 6) * 8 + xcd) * 64 + (kq & 63);
;       if (tile >= total) { d.ok = false; return; }
;       const int strip = tile / (MT * 8), rem = tile - strip * (MT * 8);
;       const int wdt = min(8, nvt - strip * 8);
;       const int mt = rem / wdt, vt = vlo + strip * 8 + rem % wdt;
;       d.nt = kind == 0 ? nt_map0(vt) : vt; d.m0 = mt * 128; d.n0 = d.nt * 256;
;       if (kind == 0) { d.A = (const bfu*)(G + L0_H) + (long)d.m0 * 2048; d.Bt = P_WA + (long)d.n0 * 2048; d.K = 2048; }
.LBB0_919:
	s_or_b64 exec, exec, s[2:3]
	s_waitcnt lgkmcnt(0)
	s_barrier
	ds_read_b32 v0, v191
	v_mov_b32_e32 v242, 0xff800000
	v_mov_b32_e32 v214, 0x7fc00000
	v_mov_b32_e32 v209, 0x7f800000
	v_mov_b32_e32 v201, 0x3ecc95a3
	s_waitcnt lgkmcnt(0)
	v_readfirstlane_b32 s2, v0
	s_and_b32 s3, s2, 0xfffffff8
	s_or_b32 s3, s3, s33
	s_and_b32 s2, s2, 7
	s_lshl_b32 s3, s3, 3
	s_or_b32 s4, s3, s2
	s_cmpk_lt_i32 s4, 0x3f0
	s_cselect_b64 s[2:3], -1, 0
	s_cmpk_gt_i32 s4, 0x3ef
	s_cbranch_scc1 .LBB0_921
	s_mul_hi_i32 s5, s4, 0x38e38e39
	s_lshr_b32 s6, s5, 31
	s_ashr_i32 s5, s5, 6
	s_add_i32 s5, s5, s6
	s_lshl_b32 s6, s5, 3
	s_sub_i32 s7, 28, s6
	s_min_u32 s7, s7, 8
	v_cvt_f32_ubyte0_e32 v0, s7
	v_rcp_iflag_f32_e32 v0, v0
	s_sub_i32 s9, 0, s7
	s_mulk_i32 s5, 0xfee0
	s_add_i32 s5, s5, s4
	v_mul_f32_e32 v0, 0x4f7ffffe, v0
	v_cvt_u32_f32_e32 v0, v0
	s_abs_i32 s8, s5
	s_ashr_i32 s4, s5, 31
	v_readfirstlane_b32 s10, v0
	s_mul_i32 s9, s9, s10
	s_mul_hi_u32 s9, s10, s9
	s_add_i32 s10, s10, s9
	s_mul_hi_u32 s9, s8, s10
	s_mul_i32 s10, s9, s7
	s_sub_i32 s8, s8, s10
	s_add_i32 s10, s9, 1
	s_sub_i32 s11, s8, s7
	s_cmp_ge_u32 s8, s7
	s_cselect_b32 s9, s10, s9
	s_cselect_b32 s8, s11, s8
	s_add_i32 s10, s9, 1
	s_cmp_ge_u32 s8, s7
	s_cselect_b32 s8, s10, s9
	s_xor_b32 s8, s8, s4
	s_sub_i32 s4, s8, s4
	s_mul_i32 s7, s4, s7
	s_sub_i32 s5, s5, s7
	s_add_i32 s5, s5, s6
	s_add_i32 s6, s5, 24
	s_sub_i32 s7, s5, 17
	s_cmp_lg_u32 s5, 16
	s_cselect_b32 s7, s7, 64
	s_cmp_lt_i32 s5, 16
	s_cselect_b32 s14, s6, s7
	s_lshl_b32 s38, s4, 7
	s_ashr_i32 s39, s38, 31
	s_lshl_b32 s40, s14, 8
	s_lshl_b64 s[4:5], s[38:39], 12
	s_add_u32 s4, s0, s4
	s_addc_u32 s5, s1, s5
	s_add_u32 s42, s4, 0xea00000
	s_addc_u32 s43, s5, 0
	s_ashr_i32 s41, s40, 31
	s_lshl_b64 s[4:5], s[40:41], 12
	v_readlane_b32 s6, v254, 13
	s_add_u32 s44, s6, s4
	v_readlane_b32 s4, v254, 14
	s_addc_u32 s45, s4, s5

; DI int TID() { int t = threadIdx.x; asm volatile("" : "+v"(t)); return t; }
; DI void phase_gemm(const Params& p, int g, int kind, char* smem, float* rsl, int* s_item, int vlo, int vhi, int cslot) {
;     ...
;   auto fetch = [&](TD& d) {
;     for (;;) {
;       __syncthreads();
;       if (TID() == 0) *s_item = atomicAdd(qctr, 1);
;       __syncthreads();
;       const int kq = *s_item;
;       const int tile = ((kq >> 6) * 8 + xcd) * 64 + (kq & 63);
;       if (tile >= total) { d.ok = false; return; }
;       const int strip = tile / (MT * 8), rem = tile - strip * (MT * 8);
;       const int wdt = min(8, nvt - strip * 8);
;       const int mt = rem / wdt, vt = vlo + strip * 8 + rem % wdt;
;       d.nt = kind == 0 ? nt_map0(vt) : vt; d.m0 = mt * 128; d.n0 = d.nt * 256;
;       if (kind == 0) { d.A = (const bfu*)(G + L0_H) + (long)d.m0 * 2048; d.Bt = P_WA + (long)d.n0 * 2048; d.K = 2048; }
.LBB0_933:
	s_or_b64 exec, exec, s[2:3]
	s_waitcnt lgkmcnt(0)
	s_barrier
	ds_read_b32 v128, v191
	s_waitcnt lgkmcnt(0)
	v_readfirstlane_b32 s1, v128
	s_and_b32 s2, s1, 0xfffffff8
	s_or_b32 s2, s2, s33
	s_and_b32 s1, s1, 7
	s_lshl_b32 s2, s2, 3
	s_or_b32 s1, s2, s1
	s_cmpk_lt_i32 s1, 0x3f0
	s_cselect_b64 s[2:3], -1, 0
	s_cmpk_gt_i32 s1, 0x3ef
	s_cselect_b64 s[46:47], -1, 0
	s_and_b64 vcc, exec, s[46:47]
	s_cbranch_vccnz .LBB0_935
	s_mul_hi_i32 s4, s1, 0x38e38e39
	s_lshr_b32 s5, s4, 31
	s_ashr_i32 s4, s4, 6
	s_add_i32 s4, s4, s5
	s_lshl_b32 s5, s4, 3
	s_sub_i32 s6, 28, s5
	s_min_u32 s6, s6, 8
	v_cvt_f32_ubyte0_e32 v128, s6
	v_rcp_iflag_f32_e32 v128, v128
	s_sub_i32 s11, 0, s6
	s_mulk_i32 s4, 0xfee0
	s_add_i32 s4, s4, s1
	v_mul_f32_e32 v128, 0x4f7ffffe, v128
	v_cvt_u32_f32_e32 v128, v128
	s_abs_i32 s7, s4
	s_ashr_i32 s1, s4, 31
	v_readfirstlane_b32 s12, v128
	s_mul_i32 s11, s11, s12
	s_mul_hi_u32 s11, s12, s11
	s_add_i32 s12, s12, s11
	s_mul_hi_u32 s11, s7, s12
	s_mul_i32 s12, s11, s6
	s_sub_i32 s7, s7, s12
	s_add_i32 s12, s11, 1
	s_sub_i32 s13, s7, s6
	s_cmp_ge_u32 s7, s6
	s_cselect_b32 s11, s12, s11
	s_cselect_b32 s7, s13, s7
	s_add_i32 s12, s11, 1
	s_cmp_ge_u32 s7, s6
	s_cselect_b32 s7, s12, s11
	s_xor_b32 s7, s7, s1
	s_sub_i32 s1, s7, s1
	s_mul_i32 s6, s1, s6
	s_sub_i32 s4, s4, s6
	s_add_i32 s4, s4, s5
	s_add_i32 s5, s4, 24
	s_sub_i32 s6, s4, 17
	s_cmp_lg_u32 s4, 16
	s_cselect_b32 s6, s6, 64
	s_cmp_lt_i32 s4, 16
	s_cselect_b32 s14, s5, s6
	s_lshl_b32 s38, s1, 7
	s_ashr_i32 s39, s38, 31
	s_lshl_b32 s40, s14, 8
	s_lshl_b64 s[4:5], s[38:39], 12
	s_add_u32 s42, s63, s4
	s_addc_u32 s43, s54, s5
	s_ashr_i32 s41, s40, 31
	s_lshl_b64 s[4:5], s[40:41], 12
	v_readlane_b32 s1, v254, 13
	s_add_u32 s44, s1, s4
	v_readlane_b32 s1, v254, 14
	s_addc_u32 s45, s1, s5

; DI int TID() { int t = threadIdx.x; asm volatile("" : "+v"(t)); return t; }
; DI void phase_gemm(const Params& p, int g, int kind, char* smem, float* rsl, int* s_item, int vlo, int vhi, int cslot) {
;     ...
;   auto fetch = [&](TD& d) {
;     for (;;) {
;       __syncthreads();
;       if (TID() == 0) *s_item = atomicAdd(qctr, 1);
;       __syncthreads();
;       const int kq = *s_item;
;       const int tile = ((kq >> 6) * 8 + xcd) * 64 + (kq & 63);
;       if (tile >= total) { d.ok = false; return; }
;       const int strip = tile / (MT * 8), rem = tile - strip * (MT * 8);
;       const int wdt = min(8, nvt - strip * 8);
;       const int mt = rem / wdt, vt = vlo + strip * 8 + rem % wdt;
;       d.nt = kind == 0 ? nt_map0(vt) : vt; d.m0 = mt * 128; d.n0 = d.nt * 256;
;       if (kind == 0) { d.A = (const bfu*)(G + L0_H) + (long)d.m0 * 2048; d.Bt = P_WA + (long)d.n0 * 2048; d.K = 2048; }
;       else if (kind == 1) { d.A = (const bfu*)(G + L1_H) + (long)d.m0 * 2048; d.Bt = (const bfu*)((char*)P_WA + WA_W2) + (long)d.n0 * 2048; d.K = 2048; }
.LBB0_1237:
	s_or_b64 exec, exec, s[2:3]
	s_waitcnt lgkmcnt(0)
	s_barrier
	ds_read_b32 v0, v204
	s_waitcnt lgkmcnt(0)
	v_readfirstlane_b32 s2, v0
	s_and_b32 s3, s2, 0xfffffff8
	s_or_b32 s3, s3, s33
	s_and_b32 s2, s2, 7
	s_lshl_b32 s3, s3, 3
	s_or_b32 s2, s3, s2
	s_cmpk_lt_i32 s2, 0x3f0
	s_cselect_b64 s[12:13], -1, 0
	s_cmpk_gt_i32 s2, 0x3ef
	s_cbranch_scc1 .LBB0_1239
	s_mul_hi_i32 s3, s2, 0x38e38e39
	s_lshr_b32 s4, s3, 31
	s_ashr_i32 s3, s3, 6
	s_add_i32 s3, s3, s4
	s_lshl_b32 s4, s3, 3
	s_sub_i32 s5, 28, s4
	s_min_u32 s5, s5, 8
	v_cvt_f32_ubyte0_e32 v0, s5
	v_rcp_iflag_f32_e32 v0, v0
	s_sub_i32 s7, 0, s5
	s_mulk_i32 s3, 0xfee0
	s_add_i32 s3, s3, s2
	v_mul_f32_e32 v0, 0x4f7ffffe, v0
	v_cvt_u32_f32_e32 v0, v0
	s_abs_i32 s6, s3
	s_ashr_i32 s2, s3, 31
	v_readfirstlane_b32 s8, v0
	s_mul_i32 s7, s7, s8
	s_mul_hi_u32 s7, s8, s7
	s_add_i32 s8, s8, s7
	s_mul_hi_u32 s7, s6, s8
	s_mul_i32 s8, s7, s5
	s_sub_i32 s6, s6, s8
	s_add_i32 s8, s7, 1
	s_sub_i32 s9, s6, s5
	s_cmp_ge_u32 s6, s5
	s_cselect_b32 s7, s8, s7
	s_cselect_b32 s6, s9, s6
	s_add_i32 s8, s7, 1
	s_cmp_ge_u32 s6, s5
	s_cselect_b32 s6, s8, s7
	s_xor_b32 s6, s6, s2
	s_sub_i32 s2, s6, s2
	s_mul_i32 s5, s2, s5
	s_sub_i32 s3, s3, s5
	s_add_i32 s3, s3, s4
	s_lshl_b32 s4, s2, 7
	s_ashr_i32 s5, s4, 31
	s_lshl_b32 s6, s3, 8
	s_lshl_b64 s[2:3], s[4:5], 12
	s_add_u32 s2, s0, s2
	s_addc_u32 s3, s1, s3
	s_add_u32 s8, s2, 0xb400000
	s_addc_u32 s9, s3, 0
	s_ashr_i32 s7, s6, 31
	s_lshl_b64 s[2:3], s[6:7], 12
	v_readlane_b32 s5, v254, 13
	s_add_u32 s10, s5, s2
	v_readlane_b32 s2, v254, 14
	s_addc_u32 s11, s2, s3

; DI int TID() { int t = threadIdx.x; asm volatile("" : "+v"(t)); return t; }
; DI void phase_gemm(const Params& p, int g, int kind, char* smem, float* rsl, int* s_item, int vlo, int vhi, int cslot) {
;     ...
;   auto fetch = [&](TD& d) {
;     for (;;) {
;       __syncthreads();
;       if (TID() == 0) *s_item = atomicAdd(qctr, 1);
;       __syncthreads();
;       const int kq = *s_item;
;       const int tile = ((kq >> 6) * 8 + xcd) * 64 + (kq & 63);
;       if (tile >= total) { d.ok = false; return; }
;       const int strip = tile / (MT * 8), rem = tile - strip * (MT * 8);
;       const int wdt = min(8, nvt - strip * 8);
;       const int mt = rem / wdt, vt = vlo + strip * 8 + rem % wdt;
;       d.nt = kind == 0 ? nt_map0(vt) : vt; d.m0 = mt * 128; d.n0 = d.nt * 256;
;       if (kind == 0) { d.A = (const bfu*)(G + L0_H) + (long)d.m0 * 2048; d.Bt = P_WA + (long)d.n0 * 2048; d.K = 2048; }
;       else if (kind == 1) { d.A = (const bfu*)(G + L1_H) + (long)d.m0 * 2048; d.Bt = (const bfu*)((char*)P_WA + WA_W2) + (long)d.n0 * 2048; d.K = 2048; }
.LBB0_1251:
	s_or_b64 exec, exec, s[0:1]
	s_waitcnt lgkmcnt(0)
	s_barrier
	ds_read_b32 v176, v204
	s_waitcnt lgkmcnt(0)
	v_readfirstlane_b32 s0, v176
	s_and_b32 s1, s0, 0xfffffff8
	s_or_b32 s1, s1, s33
	s_and_b32 s0, s0, 7
	s_lshl_b32 s1, s1, 3
	s_or_b32 s2, s1, s0
	s_cmpk_lt_i32 s2, 0x3f0
	s_cselect_b64 s[0:1], -1, 0
	s_cmpk_gt_i32 s2, 0x3ef
	s_cselect_b64 s[16:17], -1, 0
	s_and_b64 vcc, exec, s[16:17]
	s_cbranch_vccnz .LBB0_1253
	s_mul_hi_i32 s3, s2, 0x38e38e39
	s_lshr_b32 s4, s3, 31
	s_ashr_i32 s3, s3, 6
	s_add_i32 s3, s3, s4
	s_lshl_b32 s4, s3, 3
	s_sub_i32 s5, 28, s4
	s_min_u32 s5, s5, 8
	v_cvt_f32_ubyte0_e32 v176, s5
	v_rcp_iflag_f32_e32 v176, v176
	s_sub_i32 s7, 0, s5
	s_mulk_i32 s3, 0xfee0
	s_add_i32 s3, s3, s2
	v_mul_f32_e32 v176, 0x4f7ffffe, v176
	v_cvt_u32_f32_e32 v176, v176
	s_abs_i32 s6, s3
	s_ashr_i32 s2, s3, 31
	v_readfirstlane_b32 s8, v176
	s_mul_i32 s7, s7, s8
	s_mul_hi_u32 s7, s8, s7
	s_add_i32 s8, s8, s7
	s_mul_hi_u32 s7, s6, s8
	s_mul_i32 s8, s7, s5
	s_sub_i32 s6, s6, s8
	s_add_i32 s8, s7, 1
	s_sub_i32 s9, s6, s5
	s_cmp_ge_u32 s6, s5
	s_cselect_b32 s7, s8, s7
	s_cselect_b32 s6, s9, s6
	s_add_i32 s8, s7, 1
	s_cmp_ge_u32 s6, s5
	s_cselect_b32 s6, s8, s7
	s_xor_b32 s6, s6, s2
	s_sub_i32 s2, s6, s2
	s_mul_i32 s5, s2, s5
	s_sub_i32 s3, s3, s5
	s_add_i32 s3, s3, s4
	s_lshl_b32 s4, s2, 7
	s_ashr_i32 s5, s4, 31
	s_lshl_b32 s6, s3, 8
	s_lshl_b64 s[2:3], s[4:5], 12
	s_add_u32 s8, s38, s2
	s_addc_u32 s9, s39, s3
	s_ashr_i32 s7, s6, 31
	s_lshl_b64 s[2:3], s[6:7], 12
	v_readlane_b32 s5, v254, 13
	s_add_u32 s10, s5, s2
	v_readlane_b32 s2, v254, 14
	s_addc_u32 s11, s2, s3

; DI int TID() { int t = threadIdx.x; asm volatile("" : "+v"(t)); return t; }
; DI void phase_gemm(const Params& p, int g, int kind, char* smem, float* rsl, int* s_item, int vlo, int vhi, int cslot) {
;     ...
;   auto fetch = [&](TD& d) {
;     for (;;) {
;       __syncthreads();
;       if (TID() == 0) *s_item = atomicAdd(qctr, 1);
;       __syncthreads();
;       const int kq = *s_item;
;       const int tile = ((kq >> 6) * 8 + xcd) * 64 + (kq & 63);
;       if (tile >= total) { d.ok = false; return; }
;       const int strip = tile / (MT * 8), rem = tile - strip * (MT * 8);
;       const int wdt = min(8, nvt - strip * 8);
;       const int mt = rem / wdt, vt = vlo + strip * 8 + rem % wdt;
;       d.nt = kind == 0 ? nt_map0(vt) : vt; d.m0 = mt * 128; d.n0 = d.nt * 256;
;       if (kind == 0) { d.A = (const bfu*)(G + L0_H) + (long)d.m0 * 2048; d.Bt = P_WA + (long)d.n0 * 2048; d.K = 2048; }
;       else if (kind == 1) { d.A = (const bfu*)(G + L1_H) + (long)d.m0 * 2048; d.Bt = (const bfu*)((char*)P_WA + WA_W2) + (long)d.n0 * 2048; d.K = 2048; }
.LBB0_1559:
	s_or_b64 exec, exec, s[2:3]
	s_waitcnt lgkmcnt(0)
	s_barrier
	ds_read_b32 v0, v204
	s_waitcnt lgkmcnt(0)
	v_readfirstlane_b32 s2, v0
	s_and_b32 s3, s2, 0xfffffff8
	s_or_b32 s3, s3, s33
	s_and_b32 s2, s2, 7
	s_lshl_b32 s3, s3, 3
	s_or_b32 s2, s3, s2
	s_cmpk_lt_i32 s2, 0x240
	s_cselect_b64 s[12:13], -1, 0
	s_cmpk_gt_i32 s2, 0x23f
	s_cbranch_scc1 .LBB0_1561
	s_mul_hi_i32 s3, s2, 0x38e38e39
	s_lshr_b32 s4, s3, 31
	s_ashr_i32 s3, s3, 6
	s_add_i32 s3, s3, s4
	s_mul_i32 s4, s3, 0xfffffee0
	s_add_i32 s2, s4, s2
	s_ashr_i32 s4, s2, 31
	s_lshr_b32 s4, s4, 29
	s_add_i32 s4, s2, s4
	s_and_b32 s5, s4, -8
	s_lshl_b32 s3, s3, 3
	s_sub_i32 s2, s2, s5
	s_add_i32 s2, s3, s2
	s_add_i32 s38, s2, 28
	s_lshl_b32 s2, s4, 4
	s_and_b32 s4, s2, 0xffffff80
	s_ashr_i32 s5, s4, 31
	s_lshl_b32 s6, s38, 8
	s_lshl_b64 s[2:3], s[4:5], 12
	s_add_u32 s2, s0, s2
	s_addc_u32 s3, s1, s3
	s_add_u32 s8, s2, 0xb400000
	s_addc_u32 s9, s3, 0
	s_ashr_i32 s7, s6, 31
	s_lshl_b64 s[2:3], s[6:7], 12
	v_readlane_b32 s5, v254, 13
	s_add_u32 s10, s5, s2
	v_readlane_b32 s2, v254, 14
	s_addc_u32 s11, s2, s3

; DI int TID() { int t = threadIdx.x; asm volatile("" : "+v"(t)); return t; }
; DI void phase_gemm(const Params& p, int g, int kind, char* smem, float* rsl, int* s_item, int vlo, int vhi, int cslot) {
;     ...
;   auto fetch = [&](TD& d) {
;     for (;;) {
;       __syncthreads();
;       if (TID() == 0) *s_item = atomicAdd(qctr, 1);
;       __syncthreads();
;       const int kq = *s_item;
;       const int tile = ((kq >> 6) * 8 + xcd) * 64 + (kq & 63);
;       if (tile >= total) { d.ok = false; return; }
;       const int strip = tile / (MT * 8), rem = tile - strip * (MT * 8);
;       const int wdt = min(8, nvt - strip * 8);
;       const int mt = rem / wdt, vt = vlo + strip * 8 + rem % wdt;
;       d.nt = kind == 0 ? nt_map0(vt) : vt; d.m0 = mt * 128; d.n0 = d.nt * 256;
;       if (kind == 0) { d.A = (const bfu*)(G + L0_H) + (long)d.m0 * 2048; d.Bt = P_WA + (long)d.n0 * 2048; d.K = 2048; }
;       else if (kind == 1) { d.A = (const bfu*)(G + L1_H) + (long)d.m0 * 2048; d.Bt = (const bfu*)((char*)P_WA + WA_W2) + (long)d.n0 * 2048; d.K = 2048; }
.LBB0_1573:
	s_or_b64 exec, exec, s[0:1]
	s_waitcnt lgkmcnt(0)
	s_barrier
	ds_read_b32 v176, v204
	s_waitcnt lgkmcnt(0)
	v_readfirstlane_b32 s0, v176
	s_and_b32 s1, s0, 0xfffffff8
	s_or_b32 s1, s1, s33
	s_and_b32 s0, s0, 7
	s_lshl_b32 s1, s1, 3
	s_or_b32 s2, s1, s0
	s_cmpk_lt_i32 s2, 0x240
	s_cselect_b64 s[0:1], -1, 0
	s_cmpk_gt_i32 s2, 0x23f
	s_cselect_b64 s[16:17], -1, 0
	s_and_b64 vcc, exec, s[16:17]
	s_cbranch_vccnz .LBB0_1575
	s_mul_hi_i32 s3, s2, 0x38e38e39
	s_lshr_b32 s4, s3, 31
	s_ashr_i32 s3, s3, 6
	s_add_i32 s3, s3, s4
	s_mul_i32 s4, s3, 0xfffffee0
	s_add_i32 s2, s4, s2
	s_ashr_i32 s4, s2, 31
	s_lshr_b32 s4, s4, 29
	s_add_i32 s4, s2, s4
	s_and_b32 s5, s4, -8
	s_lshl_b32 s3, s3, 3
	s_sub_i32 s2, s2, s5
	s_add_i32 s2, s3, s2
	s_add_i32 s38, s2, 28
	s_lshl_b32 s2, s4, 4
	s_and_b32 s4, s2, 0xffffff80
	s_ashr_i32 s5, s4, 31
	s_lshl_b32 s6, s38, 8
	s_lshl_b64 s[2:3], s[4:5], 12
	s_add_u32 s8, s39, s2
	s_addc_u32 s9, s40, s3
	s_ashr_i32 s7, s6, 31
	s_lshl_b64 s[2:3], s[6:7], 12
	v_readlane_b32 s5, v254, 13
	s_add_u32 s10, s5, s2
	v_readlane_b32 s2, v254, 14
	s_addc_u32 s11, s2, s3

; DI int TID() { int t = threadIdx.x; asm volatile("" : "+v"(t)); return t; }
; DI void phase_gemm(const Params& p, int g, int kind, char* smem, float* rsl, int* s_item, int vlo, int vhi, int cslot) {
;     ...
;   auto fetch = [&](TD& d) {
;     for (;;) {
;       __syncthreads();
;       if (TID() == 0) *s_item = atomicAdd(qctr, 1);
;       __syncthreads();
;       const int kq = *s_item;
;       const int tile = ((kq >> 6) * 8 + xcd) * 64 + (kq & 63);
;       if (tile >= total) { d.ok = false; return; }
;       const int strip = tile / (MT * 8), rem = tile - strip * (MT * 8);
;       const int wdt = min(8, nvt - strip * 8);
;       const int mt = rem / wdt, vt = vlo + strip * 8 + rem % wdt;
;       d.nt = kind == 0 ? nt_map0(vt) : vt; d.m0 = mt * 128; d.n0 = d.nt * 256;
;       if (kind == 0) { d.A = (const bfu*)(G + L0_H) + (long)d.m0 * 2048; d.Bt = P_WA + (long)d.n0 * 2048; d.K = 2048; }
;       else if (kind == 1) { d.A = (const bfu*)(G + L1_H) + (long)d.m0 * 2048; d.Bt = (const bfu*)((char*)P_WA + WA_W2) + (long)d.n0 * 2048; d.K = 2048; }
;       else if (kind == 2) {
;         if (d.nt < 12) { d.A = (const bfu*)(G + L1_QL) + (long)d.m0 * 512; d.Bt = (const bfu*)((char*)P_WA + WA_UQ) + (long)d.n0 * 512; d.K = 512; }
;         else { d.n0 -= 12 * 256; d.A = (const bfu*)(G + L1_KVL) + (long)d.m0 * 256; d.Bt = (const bfu*)((char*)P_WA + WA_UKV) + (long)d.n0 * 256; d.K = 256; }
.LBB0_1729:
	s_or_b64 exec, exec, s[2:3]
	s_waitcnt lgkmcnt(0)
	s_barrier
	ds_read_b32 v0, v204
	s_waitcnt lgkmcnt(0)
	v_readfirstlane_b32 s2, v0
	s_and_b32 s3, s2, 0xfffffff8
	s_or_b32 s3, s3, s33
	s_and_b32 s2, s2, 7
	s_lshl_b32 s3, s3, 3
	s_or_b32 s2, s3, s2
	s_cmpk_lt_i32 s2, 0x3f0
	s_cselect_b64 s[14:15], -1, 0
	s_cmpk_gt_i32 s2, 0x3ef
	s_cbranch_scc1 .LBB0_1734
	s_mul_hi_i32 s3, s2, 0x38e38e39
	s_lshr_b32 s4, s3, 31
	s_ashr_i32 s3, s3, 6
	s_add_i32 s3, s3, s4
	s_lshl_b32 s4, s3, 3
	s_sub_i32 s5, 28, s4
	s_min_u32 s6, s5, 8
	v_cvt_f32_ubyte0_e32 v0, s6
	v_rcp_iflag_f32_e32 v0, v0
	s_sub_i32 s7, 0, s6
	s_mulk_i32 s3, 0xfee0
	s_add_i32 s3, s3, s2
	v_mul_f32_e32 v0, 0x4f7ffffe, v0
	v_cvt_u32_f32_e32 v0, v0
	s_abs_i32 s5, s3
	s_ashr_i32 s2, s3, 31
	v_readfirstlane_b32 s8, v0
	s_mul_i32 s7, s7, s8
	s_mul_hi_u32 s7, s8, s7
	s_add_i32 s8, s8, s7
	s_mul_hi_u32 s7, s5, s8
	s_mul_i32 s8, s7, s6
	s_sub_i32 s5, s5, s8
	s_add_i32 s8, s7, 1
	s_sub_i32 s9, s5, s6
	s_cmp_ge_u32 s5, s6
	s_cselect_b32 s7, s8, s7
	s_cselect_b32 s5, s9, s5
	s_add_i32 s8, s7, 1
	s_cmp_ge_u32 s5, s6
	s_cselect_b32 s5, s8, s7
	s_xor_b32 s5, s5, s2
	s_sub_i32 s5, s5, s2
	s_mul_i32 s2, s5, s6
	s_sub_i32 s2, s3, s2
	s_add_i32 s40, s2, s4
	s_lshl_b32 s4, s40, 8
	s_cmp_lt_i32 s40, 12
	s_cbranch_scc1 .LBB0_1732
	s_addk_i32 s4, 0xf400
	s_movk_i32 s6, 0x100
	s_mov_b64 s[12:13], 0xce80000
	s_mov_b64 s[2:3], 9
	s_mov_b64 s[10:11], 0x11280000
	s_branch .LBB0_1733

; DI int TID() { int t = threadIdx.x; asm volatile("" : "+v"(t)); return t; }
; DI void phase_gemm(const Params& p, int g, int kind, char* smem, float* rsl, int* s_item, int vlo, int vhi, int cslot) {
;     ...
;   auto fetch = [&](TD& d) {
;     for (;;) {
;       __syncthreads();
;       if (TID() == 0) *s_item = atomicAdd(qctr, 1);
;       __syncthreads();
;       const int kq = *s_item;
;       const int tile = ((kq >> 6) * 8 + xcd) * 64 + (kq & 63);
;       if (tile >= total) { d.ok = false; return; }
;       const int strip = tile / (MT * 8), rem = tile - strip * (MT * 8);
;       const int wdt = min(8, nvt - strip * 8);
;       const int mt = rem / wdt, vt = vlo + strip * 8 + rem % wdt;
;       d.nt = kind == 0 ? nt_map0(vt) : vt; d.m0 = mt * 128; d.n0 = d.nt * 256;
;       if (kind == 0) { d.A = (const bfu*)(G + L0_H) + (long)d.m0 * 2048; d.Bt = P_WA + (long)d.n0 * 2048; d.K = 2048; }
;       else if (kind == 1) { d.A = (const bfu*)(G + L1_H) + (long)d.m0 * 2048; d.Bt = (const bfu*)((char*)P_WA + WA_W2) + (long)d.n0 * 2048; d.K = 2048; }
;       else if (kind == 2) {
;         if (d.nt < 12) { d.A = (const bfu*)(G + L1_QL) + (long)d.m0 * 512; d.Bt = (const bfu*)((char*)P_WA + WA_UQ) + (long)d.n0 * 512; d.K = 512; }
;         else { d.n0 -= 12 * 256; d.A = (const bfu*)(G + L1_KVL) + (long)d.m0 * 256; d.Bt = (const bfu*)((char*)P_WA + WA_UKV) + (long)d.n0 * 256; d.K = 256; }
.LBB0_1754:
	s_or_b64 exec, exec, s[2:3]
	s_waitcnt lgkmcnt(0)
	s_barrier
	ds_read_b32 v176, v204
	s_waitcnt lgkmcnt(0)
	v_readfirstlane_b32 s2, v176
	s_and_b32 s3, s2, 0xfffffff8
	s_or_b32 s3, s3, s33
	s_and_b32 s2, s2, 7
	s_lshl_b32 s3, s3, 3
	s_or_b32 s5, s3, s2
	s_cmpk_lt_i32 s5, 0x3f0
	s_cselect_b64 s[2:3], -1, 0
	s_cmpk_gt_i32 s5, 0x3ef
	s_cselect_b64 s[18:19], -1, 0
	s_and_b64 vcc, exec, s[18:19]
	s_cbranch_vccnz .LBB0_1757
	s_mul_hi_i32 s4, s5, 0x38e38e39
	s_lshr_b32 s6, s4, 31
	s_ashr_i32 s4, s4, 6
	s_add_i32 s4, s4, s6
	s_lshl_b32 s6, s4, 3
	s_sub_i32 s7, 28, s6
	s_min_u32 s7, s7, 8
	v_cvt_f32_ubyte0_e32 v176, s7
	v_rcp_iflag_f32_e32 v176, v176
	s_sub_i32 s9, 0, s7
	s_mulk_i32 s4, 0xfee0
	s_add_i32 s4, s4, s5
	v_mul_f32_e32 v176, 0x4f7ffffe, v176
	v_cvt_u32_f32_e32 v176, v176
	s_abs_i32 s8, s4
	s_ashr_i32 s5, s4, 31
	v_readfirstlane_b32 s10, v176
	s_mul_i32 s9, s9, s10
	s_mul_hi_u32 s9, s10, s9
	s_add_i32 s10, s10, s9
	s_mul_hi_u32 s9, s8, s10
	s_mul_i32 s10, s9, s7
	s_sub_i32 s8, s8, s10
	s_add_i32 s10, s9, 1
	s_sub_i32 s11, s8, s7
	s_cmp_ge_u32 s8, s7
	s_cselect_b32 s9, s10, s9
	s_cselect_b32 s8, s11, s8
	s_add_i32 s10, s9, 1
	s_cmp_ge_u32 s8, s7
	s_cselect_b32 s8, s10, s9
	s_xor_b32 s8, s8, s5
	s_sub_i32 s5, s8, s5
	s_mul_i32 s7, s5, s7
	s_sub_i32 s4, s4, s7
	s_add_i32 s40, s4, s6
	s_lshl_b32 s4, s40, 8
	s_cmp_lt_i32 s40, 12
	s_cbranch_scc1 .LBB0_1759
	s_addk_i32 s4, 0xf400
	s_movk_i32 s6, 0x100
	s_mov_b64 s[20:21], 0xce80000
	s_mov_b64 s[10:11], 0x11280000
	s_mov_b64 s[12:13], 9
	s_branch .LBB0_1760

; DI int TID() { int t = threadIdx.x; asm volatile("" : "+v"(t)); return t; }
; DI void phase_gemm(const Params& p, int g, int kind, char* smem, float* rsl, int* s_item, int vlo, int vhi, int cslot) {
;     ...
;   auto fetch = [&](TD& d) {
;     for (;;) {
;       __syncthreads();
;       if (TID() == 0) *s_item = atomicAdd(qctr, 1);
;       __syncthreads();
;       const int kq = *s_item;
;       const int tile = ((kq >> 6) * 8 + xcd) * 64 + (kq & 63);
;       if (tile >= total) { d.ok = false; return; }
;       const int strip = tile / (MT * 8), rem = tile - strip * (MT * 8);
;       const int wdt = min(8, nvt - strip * 8);
;       const int mt = rem / wdt, vt = vlo + strip * 8 + rem % wdt;
;       d.nt = kind == 0 ? nt_map0(vt) : vt; d.m0 = mt * 128; d.n0 = d.nt * 256;
;       if (kind == 0) { d.A = (const bfu*)(G + L0_H) + (long)d.m0 * 2048; d.Bt = P_WA + (long)d.n0 * 2048; d.K = 2048; }
;       else if (kind == 1) { d.A = (const bfu*)(G + L1_H) + (long)d.m0 * 2048; d.Bt = (const bfu*)((char*)P_WA + WA_W2) + (long)d.n0 * 2048; d.K = 2048; }
;       else if (kind == 2) {
;         if (d.nt < 12) { d.A = (const bfu*)(G + L1_QL) + (long)d.m0 * 512; d.Bt = (const bfu*)((char*)P_WA + WA_UQ) + (long)d.n0 * 512; d.K = 512; }
;         else { d.n0 -= 12 * 256; d.A = (const bfu*)(G + L1_KVL) + (long)d.m0 * 256; d.Bt = (const bfu*)((char*)P_WA + WA_UKV) + (long)d.n0 * 256; d.K = 256; }
;       } else {
;         const int layer = kind - 3;
;         if (layer == 1 && (d.m0 % T) < CTX) continue;
;         d.A = (const bfu*)(G + (layer == 0 ? L0_MIX : L1_MIX)) + (long)d.m0 * 4096;
;         d.Bt = (layer == 0 ? P_WO1 : (const bfu*)((char*)P_WA + WA_WO2)) + (long)d.n0 * 4096; d.K = 4096;
;       }
.LBB0_2181:
	s_or_b64 exec, exec, s[2:3]
	s_waitcnt lgkmcnt(0)
	s_barrier
	ds_read_b32 v0, v204
	s_mov_b64 s[4:5], -1
	s_waitcnt lgkmcnt(0)
	v_readfirstlane_b32 s2, v0
	s_and_b32 s3, s2, 0xfffffff8
	s_or_b32 s3, s3, s33
	s_and_b32 s2, s2, 7
	s_lshl_b32 s3, s3, 3
	s_or_b32 s10, s3, s2
	s_mov_b64 s[2:3], -1
	s_cmpk_gt_i32 s10, 0x11f
	s_cbranch_scc1 .LBB0_2176
	s_mul_hi_i32 s2, s10, 0x38e38e39
	s_lshr_b32 s3, s2, 31
	s_ashr_i32 s2, s2, 6
	s_add_i32 s6, s2, s3
	s_mul_i32 s2, s6, 0xfffffee0
	s_add_i32 s7, s2, s10
	s_ashr_i32 s2, s7, 31
	s_lshr_b32 s2, s2, 29
	s_add_i32 s2, s7, s2
	s_ashr_i32 s9, s2, 3
	s_lshl_b32 s8, s9, 7
	s_mul_hi_i32 s2, s8, 0x38e38e39
	s_lshr_b32 s3, s2, 31
	s_ashr_i32 s2, s2, 9
	s_add_i32 s2, s2, s3
	s_mulk_i32 s2, 0x900
	s_sub_i32 s4, s8, s2
	s_cmpk_gt_i32 s4, 0xff
	s_mov_b64 s[2:3], 0
	s_cselect_b64 s[4:5], -1, 0
	s_branch .LBB0_2176

; DI int TID() { int t = threadIdx.x; asm volatile("" : "+v"(t)); return t; }
; DI void phase_gemm(const Params& p, int g, int kind, char* smem, float* rsl, int* s_item, int vlo, int vhi, int cslot) {
;     ...
;   auto fetch = [&](TD& d) {
;     for (;;) {
;       __syncthreads();
;       if (TID() == 0) *s_item = atomicAdd(qctr, 1);
;       __syncthreads();
;       const int kq = *s_item;
;       const int tile = ((kq >> 6) * 8 + xcd) * 64 + (kq & 63);
;       if (tile >= total) { d.ok = false; return; }
;       const int strip = tile / (MT * 8), rem = tile - strip * (MT * 8);
;       const int wdt = min(8, nvt - strip * 8);
;       const int mt = rem / wdt, vt = vlo + strip * 8 + rem % wdt;
;       d.nt = kind == 0 ? nt_map0(vt) : vt; d.m0 = mt * 128; d.n0 = d.nt * 256;
;       if (kind == 0) { d.A = (const bfu*)(G + L0_H) + (long)d.m0 * 2048; d.Bt = P_WA + (long)d.n0 * 2048; d.K = 2048; }
;       else if (kind == 1) { d.A = (const bfu*)(G + L1_H) + (long)d.m0 * 2048; d.Bt = (const bfu*)((char*)P_WA + WA_W2) + (long)d.n0 * 2048; d.K = 2048; }
;       else if (kind == 2) {
;         if (d.nt < 12) { d.A = (const bfu*)(G + L1_QL) + (long)d.m0 * 512; d.Bt = (const bfu*)((char*)P_WA + WA_UQ) + (long)d.n0 * 512; d.K = 512; }
;         else { d.n0 -= 12 * 256; d.A = (const bfu*)(G + L1_KVL) + (long)d.m0 * 256; d.Bt = (const bfu*)((char*)P_WA + WA_UKV) + (long)d.n0 * 256; d.K = 256; }
;       } else {
;         const int layer = kind - 3;
;         if (layer == 1 && (d.m0 % T) < CTX) continue;
;         d.A = (const bfu*)(G + (layer == 0 ? L0_MIX : L1_MIX)) + (long)d.m0 * 4096;
;         d.Bt = (layer == 0 ? P_WO1 : (const bfu*)((char*)P_WA + WA_WO2)) + (long)d.n0 * 4096; d.K = 4096;
;       }
.LBB0_2193:
	s_or_b64 exec, exec, s[10:11]
	s_waitcnt lgkmcnt(0)
	s_barrier
	ds_read_b32 v176, v204
	s_mov_b64 s[14:15], -1
	s_mov_b64 s[16:17], -1
	s_waitcnt lgkmcnt(0)
	v_readfirstlane_b32 s7, v176
	s_and_b32 s9, s7, 0xfffffff8
	s_or_b32 s9, s9, s33
	s_and_b32 s7, s7, 7
	s_lshl_b32 s9, s9, 3
	s_or_b32 s7, s9, s7
	s_cmpk_gt_i32 s7, 0x11f
	s_cbranch_scc1 .LBB0_2195
	s_mul_hi_i32 s9, s7, 0x38e38e39
	s_lshr_b32 s10, s9, 31
	s_ashr_i32 s9, s9, 6
	s_add_i32 s9, s9, s10
	s_mul_i32 s10, s9, 0xfffffee0
	s_add_i32 s7, s10, s7
	s_ashr_i32 s10, s7, 31
	s_lshr_b32 s10, s10, 29
	s_add_i32 s10, s7, s10
	s_and_b32 s11, s10, 0xfffff8
	s_sub_i32 s7, s7, s11
	s_lshl_b32 s10, s10, 4
	s_and_b32 s10, s10, 0xffffff80
	s_lshl_b32 s9, s9, 11
	s_lshl_b32 s7, s7, 8
	s_add_i32 s12, s9, s7
	s_mul_hi_i32 s7, s10, 0x38e38e39
	s_lshr_b32 s9, s7, 31
	s_ashr_i32 s7, s7, 9
	s_add_i32 s7, s7, s9
	s_mulk_i32 s7, 0x900
	s_sub_i32 s7, s10, s7
	s_cmpk_gt_i32 s7, 0xff
	s_mov_b64 s[14:15], 0
	s_cselect_b64 s[16:17], -1, 0
